# attention tiles run at default priority (s_setprio pairs removed): the scan wave keeps its priority 2
# baseline (speedup 1.0000x reference)
.LBB0_462:
	ds_read_b128 v[160:163], v104 offset:0
	ds_read_b128 v[164:167], v104 offset:3328
	ds_read_b128 v[168:171], v104 offset:6656
	ds_read_b128 v[172:175], v104 offset:9984
	ds_read_b128 v[224:227], v104 offset:64
	ds_read_b128 v[228:231], v104 offset:3392
	ds_read_b128 v[232:235], v104 offset:6720
	ds_read_b128 v[236:239], v104 offset:10048
	s_waitcnt lgkmcnt(6)
	v_mfma_f32_16x16x32_bf16 v[124:127], v[160:163], v[0:3], -4.0
	v_mfma_f32_16x16x32_bf16 v[128:131], v[160:163], v[12:15], -4.0
	ds_read_b128 v[160:163], v104 offset:128
	v_mfma_f32_16x16x32_bf16 v[132:135], v[164:167], v[0:3], -4.0
	v_mfma_f32_16x16x32_bf16 v[136:139], v[164:167], v[12:15], -4.0
	ds_read_b128 v[164:167], v104 offset:3456
	s_waitcnt lgkmcnt(6)
	v_mfma_f32_16x16x32_bf16 v[140:143], v[168:171], v[0:3], -4.0
	v_mfma_f32_16x16x32_bf16 v[144:147], v[168:171], v[12:15], -4.0
	ds_read_b128 v[168:171], v104 offset:6784
	v_mfma_f32_16x16x32_bf16 v[148:151], v[172:175], v[0:3], -4.0
	v_mfma_f32_16x16x32_bf16 v[152:155], v[172:175], v[12:15], -4.0
	ds_read_b128 v[172:175], v104 offset:10112
	s_waitcnt lgkmcnt(6)
	v_mfma_f32_16x16x32_bf16 v[124:127], v[224:227], v[4:7], v[124:127]
	v_mfma_f32_16x16x32_bf16 v[128:131], v[224:227], v[16:19], v[128:131]
	ds_read_b64 v[224:225], v219 offset:13312
	ds_read_b64 v[226:227], v219 offset:13344
	v_mfma_f32_16x16x32_bf16 v[132:135], v[228:231], v[4:7], v[132:135]
	v_mfma_f32_16x16x32_bf16 v[136:139], v[228:231], v[16:19], v[136:139]
	ds_read_b64 v[228:229], v219 offset:15616
	ds_read_b64 v[230:231], v219 offset:15648
	s_waitcnt lgkmcnt(8)
	v_mfma_f32_16x16x32_bf16 v[140:143], v[232:235], v[4:7], v[140:143]
	v_mfma_f32_16x16x32_bf16 v[144:147], v[232:235], v[16:19], v[144:147]
	ds_read_b64 v[232:233], v219 offset:17920
	ds_read_b64 v[234:235], v219 offset:17952
	v_mfma_f32_16x16x32_bf16 v[148:151], v[236:239], v[4:7], v[148:151]
	v_mfma_f32_16x16x32_bf16 v[152:155], v[236:239], v[16:19], v[152:155]
	ds_read_b64 v[236:237], v219 offset:20224
	ds_read_b64 v[238:239], v219 offset:20256
	s_waitcnt lgkmcnt(10)
	v_mfma_f32_16x16x32_bf16 v[124:127], v[160:163], v[8:11], v[124:127]
	v_mfma_f32_16x16x32_bf16 v[128:131], v[160:163], v[20:23], v[128:131]
	ds_read_b64 v[160:161], v219 offset:13376
	ds_read_b64 v[162:163], v219 offset:13408
	v_mfma_f32_16x16x32_bf16 v[132:135], v[164:167], v[8:11], v[132:135]
	v_mfma_f32_16x16x32_bf16 v[136:139], v[164:167], v[20:23], v[136:139]
	ds_read_b64 v[164:165], v219 offset:15680
	ds_read_b64 v[166:167], v219 offset:15712
	s_waitcnt lgkmcnt(12)
	v_mfma_f32_16x16x32_bf16 v[140:143], v[168:171], v[8:11], v[140:143]
	v_mfma_f32_16x16x32_bf16 v[144:147], v[168:171], v[20:23], v[144:147]
	ds_read_b64 v[168:169], v219 offset:17984
	ds_read_b64 v[170:171], v219 offset:18016
	v_mfma_f32_16x16x32_bf16 v[148:151], v[172:175], v[8:11], v[148:151]
	v_mfma_f32_16x16x32_bf16 v[152:155], v[172:175], v[20:23], v[152:155]
	ds_read_b64 v[172:173], v219 offset:20288
	ds_read_b64 v[174:175], v219 offset:20320
	v_exp_f32_e32 v124, v124
	v_exp_f32_e32 v125, v125
	v_exp_f32_e32 v126, v126
	v_exp_f32_e32 v127, v127
	v_add_f32_e32 v118, v118, v124
	v_add_f32_e32 v119, v119, v125
	v_exp_f32_e32 v128, v128
	v_exp_f32_e32 v129, v129
	v_add_f32_e32 v118, v118, v126
	v_add_f32_e32 v119, v119, v127
	v_exp_f32_e32 v130, v130
	v_exp_f32_e32 v131, v131
	v_add_f32_e32 v176, v176, v128
	v_add_f32_e32 v177, v177, v129
	v_exp_f32_e32 v132, v132
	v_exp_f32_e32 v133, v133
	v_add_f32_e32 v176, v176, v130
	v_add_f32_e32 v177, v177, v131
	v_exp_f32_e32 v134, v134
	v_exp_f32_e32 v135, v135
	v_add_f32_e32 v118, v118, v132
	v_add_f32_e32 v119, v119, v133
	v_exp_f32_e32 v136, v136
	v_exp_f32_e32 v137, v137
	v_add_f32_e32 v118, v118, v134
	v_add_f32_e32 v119, v119, v135
	v_exp_f32_e32 v138, v138
	v_exp_f32_e32 v139, v139
	v_add_f32_e32 v176, v176, v136
	v_add_f32_e32 v177, v177, v137
	v_cvt_pk_bf16_f32 v240, v124, v125
	v_add_f32_e32 v176, v176, v138
	v_add_f32_e32 v177, v177, v139
	v_cvt_pk_bf16_f32 v241, v126, v127
	v_cvt_pk_bf16_f32 v242, v132, v133
	v_cvt_pk_bf16_f32 v243, v134, v135
	v_cvt_pk_bf16_f32 v244, v128, v129
	v_cvt_pk_bf16_f32 v245, v130, v131
	v_cvt_pk_bf16_f32 v246, v136, v137
	v_cvt_pk_bf16_f32 v247, v138, v139
	s_waitcnt lgkmcnt(12)
	v_mfma_f32_16x16x32_bf16 v[92:95], v[224:227], v[240:243], v[92:95]
	v_exp_f32_e32 v140, v140
	v_exp_f32_e32 v141, v141
	v_exp_f32_e32 v142, v142
	v_exp_f32_e32 v143, v143
	v_add_f32_e32 v118, v118, v140
	v_mfma_f32_16x16x32_bf16 v[84:87], v[224:227], v[244:247], v[84:87]
	v_add_f32_e32 v119, v119, v141
	v_exp_f32_e32 v144, v144
	v_exp_f32_e32 v145, v145
	v_add_f32_e32 v118, v118, v142
	v_add_f32_e32 v119, v119, v143
	v_mfma_f32_16x16x32_bf16 v[88:91], v[228:231], v[240:243], v[88:91]
	v_exp_f32_e32 v146, v146
	v_exp_f32_e32 v147, v147
	v_add_f32_e32 v176, v176, v144
	v_add_f32_e32 v177, v177, v145
	v_exp_f32_e32 v148, v148
	v_mfma_f32_16x16x32_bf16 v[76:79], v[228:231], v[244:247], v[76:79]
	v_exp_f32_e32 v149, v149
	v_add_f32_e32 v176, v176, v146
	v_add_f32_e32 v177, v177, v147
	v_exp_f32_e32 v150, v150
	v_exp_f32_e32 v151, v151
	s_waitcnt lgkmcnt(8)
	v_mfma_f32_16x16x32_bf16 v[80:83], v[232:235], v[240:243], v[80:83]
	v_add_f32_e32 v118, v118, v148
	v_add_f32_e32 v119, v119, v149
	v_exp_f32_e32 v152, v152
	v_exp_f32_e32 v153, v153
	v_add_f32_e32 v118, v118, v150
	v_mfma_f32_16x16x32_bf16 v[68:71], v[232:235], v[244:247], v[68:71]
	v_add_f32_e32 v119, v119, v151
	v_exp_f32_e32 v154, v154
	v_exp_f32_e32 v155, v155
	v_add_f32_e32 v176, v176, v152
	v_add_f32_e32 v177, v177, v153
	v_mfma_f32_16x16x32_bf16 v[72:75], v[236:239], v[240:243], v[72:75]
	v_cvt_pk_bf16_f32 v96, v140, v141
	v_add_f32_e32 v176, v176, v154
	v_add_f32_e32 v177, v177, v155
	v_cvt_pk_bf16_f32 v97, v142, v143
	v_cvt_pk_bf16_f32 v98, v148, v149
	v_mfma_f32_16x16x32_bf16 v[64:67], v[236:239], v[244:247], v[64:67]
	v_cvt_pk_bf16_f32 v99, v150, v151
	v_cvt_pk_bf16_f32 v100, v144, v145
	v_cvt_pk_bf16_f32 v101, v146, v147
	v_cvt_pk_bf16_f32 v102, v152, v153
	v_cvt_pk_bf16_f32 v103, v154, v155
	s_nop 1
	s_waitcnt lgkmcnt(4)
	v_mfma_f32_16x16x32_bf16 v[92:95], v[160:163], v[96:99], v[92:95]
	v_mfma_f32_16x16x32_bf16 v[84:87], v[160:163], v[100:103], v[84:87]
	v_mfma_f32_16x16x32_bf16 v[88:91], v[164:167], v[96:99], v[88:91]
	v_mfma_f32_16x16x32_bf16 v[76:79], v[164:167], v[100:103], v[76:79]
	s_waitcnt lgkmcnt(0)
	v_mfma_f32_16x16x32_bf16 v[80:83], v[168:171], v[96:99], v[80:83]
	v_mfma_f32_16x16x32_bf16 v[68:71], v[168:171], v[100:103], v[68:71]
	v_mfma_f32_16x16x32_bf16 v[72:75], v[172:175], v[96:99], v[72:75]
	v_mfma_f32_16x16x32_bf16 v[64:67], v[172:175], v[100:103], v[64:67]
	s_add_i32 s44, s42, -2
	s_cmp_ge_u32 s44, s35
	s_cbranch_scc1 .LBB0_464
	s_waitcnt vmcnt(4)
	ds_write_b128 v115, v[24:27] offset:22528
	s_waitcnt vmcnt(3)
	ds_write_b128 v117, v[28:31] offset:22528
	s_waitcnt vmcnt(1)
	ds_write_b128 v217, v[36:39] offset:22528
	ds_write_b128 v218, v[32:35] offset:35840
	s_waitcnt vmcnt(0)
	ds_write_b128 v218, v[40:43] offset:40448

.LBB0_466:
	ds_read_b128 v[160:163], v104 offset:22528
	ds_read_b128 v[164:167], v104 offset:25856
	ds_read_b128 v[168:171], v104 offset:29184
	ds_read_b128 v[172:175], v104 offset:32512
	ds_read_b128 v[224:227], v104 offset:22592
	ds_read_b128 v[228:231], v104 offset:25920
	ds_read_b128 v[232:235], v104 offset:29248
	ds_read_b128 v[236:239], v104 offset:32576
	s_waitcnt lgkmcnt(6)
	v_mfma_f32_16x16x32_bf16 v[124:127], v[160:163], v[0:3], -4.0
	v_mfma_f32_16x16x32_bf16 v[128:131], v[160:163], v[12:15], -4.0
	ds_read_b128 v[160:163], v104 offset:22656
	v_mfma_f32_16x16x32_bf16 v[132:135], v[164:167], v[0:3], -4.0
	v_mfma_f32_16x16x32_bf16 v[136:139], v[164:167], v[12:15], -4.0
	ds_read_b128 v[164:167], v104 offset:25984
	s_waitcnt lgkmcnt(6)
	v_mfma_f32_16x16x32_bf16 v[140:143], v[168:171], v[0:3], -4.0
	v_mfma_f32_16x16x32_bf16 v[144:147], v[168:171], v[12:15], -4.0
	ds_read_b128 v[168:171], v104 offset:29312
	v_mfma_f32_16x16x32_bf16 v[148:151], v[172:175], v[0:3], -4.0
	v_mfma_f32_16x16x32_bf16 v[152:155], v[172:175], v[12:15], -4.0
	ds_read_b128 v[172:175], v104 offset:32640
	s_waitcnt lgkmcnt(6)
	v_mfma_f32_16x16x32_bf16 v[124:127], v[224:227], v[4:7], v[124:127]
	v_mfma_f32_16x16x32_bf16 v[128:131], v[224:227], v[16:19], v[128:131]
	ds_read_b64 v[224:225], v219 offset:35840
	ds_read_b64 v[226:227], v219 offset:35872
	v_mfma_f32_16x16x32_bf16 v[132:135], v[228:231], v[4:7], v[132:135]
	v_mfma_f32_16x16x32_bf16 v[136:139], v[228:231], v[16:19], v[136:139]
	ds_read_b64 v[228:229], v219 offset:38144
	ds_read_b64 v[230:231], v219 offset:38176
	s_waitcnt lgkmcnt(8)
	v_mfma_f32_16x16x32_bf16 v[140:143], v[232:235], v[4:7], v[140:143]
	v_mfma_f32_16x16x32_bf16 v[144:147], v[232:235], v[16:19], v[144:147]
	ds_read_b64 v[232:233], v219 offset:40448
	ds_read_b64 v[234:235], v219 offset:40480
	v_mfma_f32_16x16x32_bf16 v[148:151], v[236:239], v[4:7], v[148:151]
	v_mfma_f32_16x16x32_bf16 v[152:155], v[236:239], v[16:19], v[152:155]
	ds_read_b64 v[236:237], v219 offset:42752
	ds_read_b64 v[238:239], v219 offset:42784
	s_waitcnt lgkmcnt(10)
	v_mfma_f32_16x16x32_bf16 v[124:127], v[160:163], v[8:11], v[124:127]
	v_mfma_f32_16x16x32_bf16 v[128:131], v[160:163], v[20:23], v[128:131]
	ds_read_b64 v[160:161], v219 offset:35904
	ds_read_b64 v[162:163], v219 offset:35936
	v_mfma_f32_16x16x32_bf16 v[132:135], v[164:167], v[8:11], v[132:135]
	v_mfma_f32_16x16x32_bf16 v[136:139], v[164:167], v[20:23], v[136:139]
	ds_read_b64 v[164:165], v219 offset:38208
	ds_read_b64 v[166:167], v219 offset:38240
	s_waitcnt lgkmcnt(12)
	v_mfma_f32_16x16x32_bf16 v[140:143], v[168:171], v[8:11], v[140:143]
	v_mfma_f32_16x16x32_bf16 v[144:147], v[168:171], v[20:23], v[144:147]
	ds_read_b64 v[168:169], v219 offset:40512
	ds_read_b64 v[170:171], v219 offset:40544
	v_mfma_f32_16x16x32_bf16 v[148:151], v[172:175], v[8:11], v[148:151]
	v_mfma_f32_16x16x32_bf16 v[152:155], v[172:175], v[20:23], v[152:155]
	ds_read_b64 v[172:173], v219 offset:42816
	ds_read_b64 v[174:175], v219 offset:42848
	v_exp_f32_e32 v124, v124
	v_exp_f32_e32 v125, v125
	v_exp_f32_e32 v126, v126
	v_exp_f32_e32 v127, v127
	v_add_f32_e32 v118, v118, v124
	v_add_f32_e32 v119, v119, v125
	v_exp_f32_e32 v128, v128
	v_exp_f32_e32 v129, v129
	v_add_f32_e32 v118, v118, v126
	v_add_f32_e32 v119, v119, v127
	v_exp_f32_e32 v130, v130
	v_exp_f32_e32 v131, v131
	v_add_f32_e32 v176, v176, v128
	v_add_f32_e32 v177, v177, v129
	v_exp_f32_e32 v132, v132
	v_exp_f32_e32 v133, v133
	v_add_f32_e32 v176, v176, v130
	v_add_f32_e32 v177, v177, v131
	v_exp_f32_e32 v134, v134
	v_exp_f32_e32 v135, v135
	v_add_f32_e32 v118, v118, v132
	v_add_f32_e32 v119, v119, v133
	v_exp_f32_e32 v136, v136
	v_exp_f32_e32 v137, v137
	v_add_f32_e32 v118, v118, v134
	v_add_f32_e32 v119, v119, v135
	v_exp_f32_e32 v138, v138
	v_exp_f32_e32 v139, v139
	v_add_f32_e32 v176, v176, v136
	v_add_f32_e32 v177, v177, v137
	v_cvt_pk_bf16_f32 v240, v124, v125
	v_add_f32_e32 v176, v176, v138
	v_add_f32_e32 v177, v177, v139
	v_cvt_pk_bf16_f32 v241, v126, v127
	v_cvt_pk_bf16_f32 v242, v132, v133
	v_cvt_pk_bf16_f32 v243, v134, v135
	v_cvt_pk_bf16_f32 v244, v128, v129
	v_cvt_pk_bf16_f32 v245, v130, v131
	v_cvt_pk_bf16_f32 v246, v136, v137
	v_cvt_pk_bf16_f32 v247, v138, v139
	s_waitcnt lgkmcnt(12)
	v_mfma_f32_16x16x32_bf16 v[92:95], v[224:227], v[240:243], v[92:95]
	v_exp_f32_e32 v140, v140
	v_exp_f32_e32 v141, v141
	v_exp_f32_e32 v142, v142
	v_exp_f32_e32 v143, v143
	v_add_f32_e32 v118, v118, v140
	v_mfma_f32_16x16x32_bf16 v[84:87], v[224:227], v[244:247], v[84:87]
	v_add_f32_e32 v119, v119, v141
	v_exp_f32_e32 v144, v144
	v_exp_f32_e32 v145, v145
	v_add_f32_e32 v118, v118, v142
	v_add_f32_e32 v119, v119, v143
	v_mfma_f32_16x16x32_bf16 v[88:91], v[228:231], v[240:243], v[88:91]
	v_exp_f32_e32 v146, v146
	v_exp_f32_e32 v147, v147
	v_add_f32_e32 v176, v176, v144
	v_add_f32_e32 v177, v177, v145
	v_exp_f32_e32 v148, v148
	v_mfma_f32_16x16x32_bf16 v[76:79], v[228:231], v[244:247], v[76:79]
	v_exp_f32_e32 v149, v149
	v_add_f32_e32 v176, v176, v146
	v_add_f32_e32 v177, v177, v147
	v_exp_f32_e32 v150, v150
	v_exp_f32_e32 v151, v151
	s_waitcnt lgkmcnt(8)
	v_mfma_f32_16x16x32_bf16 v[80:83], v[232:235], v[240:243], v[80:83]
	v_add_f32_e32 v118, v118, v148
	v_add_f32_e32 v119, v119, v149
	v_exp_f32_e32 v152, v152
	v_exp_f32_e32 v153, v153
	v_add_f32_e32 v118, v118, v150
	v_mfma_f32_16x16x32_bf16 v[68:71], v[232:235], v[244:247], v[68:71]
	v_add_f32_e32 v119, v119, v151
	v_exp_f32_e32 v154, v154
	v_exp_f32_e32 v155, v155
	v_add_f32_e32 v176, v176, v152
	v_add_f32_e32 v177, v177, v153
	v_mfma_f32_16x16x32_bf16 v[72:75], v[236:239], v[240:243], v[72:75]
	v_cvt_pk_bf16_f32 v96, v140, v141
	v_add_f32_e32 v176, v176, v154
	v_add_f32_e32 v177, v177, v155
	v_cvt_pk_bf16_f32 v97, v142, v143
	v_cvt_pk_bf16_f32 v98, v148, v149
	v_mfma_f32_16x16x32_bf16 v[64:67], v[236:239], v[244:247], v[64:67]
	v_cvt_pk_bf16_f32 v99, v150, v151
	v_cvt_pk_bf16_f32 v100, v144, v145
	v_cvt_pk_bf16_f32 v101, v146, v147
	v_cvt_pk_bf16_f32 v102, v152, v153
	v_cvt_pk_bf16_f32 v103, v154, v155
	s_nop 1
	s_waitcnt lgkmcnt(4)
	v_mfma_f32_16x16x32_bf16 v[92:95], v[160:163], v[96:99], v[92:95]
	v_mfma_f32_16x16x32_bf16 v[84:87], v[160:163], v[100:103], v[84:87]
	v_mfma_f32_16x16x32_bf16 v[88:91], v[164:167], v[96:99], v[88:91]
	v_mfma_f32_16x16x32_bf16 v[76:79], v[164:167], v[100:103], v[76:79]
	s_waitcnt lgkmcnt(0)
	v_mfma_f32_16x16x32_bf16 v[80:83], v[168:171], v[96:99], v[80:83]
	v_mfma_f32_16x16x32_bf16 v[68:71], v[168:171], v[100:103], v[68:71]
	v_mfma_f32_16x16x32_bf16 v[72:75], v[172:175], v[96:99], v[72:75]
	v_mfma_f32_16x16x32_bf16 v[64:67], v[172:175], v[100:103], v[64:67]
	s_andn2_b64 vcc, exec, s[0:1]
	s_cbranch_vccnz .LBB0_459
	s_waitcnt vmcnt(4)
	ds_write_b128 v115, v[44:47]
	s_waitcnt vmcnt(3)
	ds_write_b128 v117, v[48:51]
	s_waitcnt vmcnt(2)
	ds_write_b128 v217, v[52:55]
	s_waitcnt vmcnt(1)
	ds_write_b128 v218, v[56:59] offset:13312
	s_waitcnt vmcnt(0)
	ds_write_b128 v218, v[60:63] offset:17920
	s_branch .LBB0_459
